# speedup vs baseline: 1.0048x; 1.0040x over previous
; __device__ __forceinline__ unsigned pack2(float a, float b) { return (unsigned)f2bf(a) | ((unsigned)f2bf(b) << 16); }
; template <int DH, int MODE>
; __device__ void attn_item(const Params& p, int layer, int b, int blk, int head, char* smem) {
;     ...
;         float other = __shfl_xor(run, 1);
;         float offs = m_run + (half == 0 ? other : 0.f);
; #pragma unroll 2
;         for (int s8 = 0; s8 < 4; ++s8) {
;           float4 va = s4[2 * s8], vb = s4[2 * s8 + 1];
;           float e[8] = {va.x, va.y, va.z, va.w, vb.x, vb.y, vb.z, vb.w};
;           float pv[8];
; #pragma unroll
;           for (int k = 0; k < 8; ++k) {
;             bool valid = (kpb + s8 * 8 + k) < qpos;
;             pv[k] = valid ? __builtin_amdgcn_exp2f(e[k] + offs) : 0.f;
;           }
;           uint4 ov;
;           ov.x = pack2(pv[0], pv[1]); ov.y = pack2(pv[2], pv[3]);
;           ov.z = pack2(pv[4], pv[5]); ov.w = pack2(pv[6], pv[7]);
;           *reinterpret_cast<uint4*>(prow + s8 * 16) = ov;
;         }
.Lsb_p1done_3:
	ds_bpermute_b32 v147, v163, v146
	s_mov_b32 s85, 0
	v_mov_b32_e32 v175, v168
	v_mov_b32_e32 v177, v167
	s_waitcnt lgkmcnt(0)
	v_cndmask_b32_e64 v148, 0, v147, s[6:7]
	v_add_f32_e32 v176, v174, v148
	v_sub_u32_e32 v212, v144, v173
	v_add_u32_e32 v212, 0xffffc040, v212
	v_cmp_lt_i32_e32 vcc, 31, v212
	s_cmp_eq_u64 vcc, exec
	s_cbranch_scc1 .Lsb_p2fast_3
	v_add_f32_e32 v180, v176, v180
	v_add_f32_e32 v181, v176, v181
	v_add_f32_e32 v182, v176, v182
	v_exp_f32_e32 v180, v180
	v_exp_f32_e32 v181, v181
	v_exp_f32_e32 v182, v182
	v_cmp_lt_i32_e32 vcc, 0, v212
	v_cmp_lt_i32_e64 s[92:93], 1, v212
	v_cmp_lt_i32_e64 s[94:95], 2, v212
	v_cndmask_b32_e32 v180, 0, v180, vcc
	v_cndmask_b32_e64 v181, 0, v181, s[92:93]
	v_cndmask_b32_e64 v182, 0, v182, s[94:95]
	v_add_f32_e32 v183, v176, v183
	v_add_f32_e32 v184, v176, v184
	v_add_f32_e32 v185, v176, v185
	v_exp_f32_e32 v183, v183
	v_exp_f32_e32 v184, v184
	v_exp_f32_e32 v185, v185
	v_cmp_lt_i32_e32 vcc, 3, v212
	v_cmp_lt_i32_e64 s[92:93], 4, v212
	v_cmp_lt_i32_e64 s[94:95], 5, v212
	v_cndmask_b32_e32 v183, 0, v183, vcc
	v_cndmask_b32_e64 v184, 0, v184, s[92:93]
	v_cndmask_b32_e64 v185, 0, v185, s[94:95]
	v_add_f32_e32 v186, v176, v186
	v_add_f32_e32 v187, v176, v187
	v_add_f32_e32 v188, v176, v188
	v_exp_f32_e32 v186, v186
	v_exp_f32_e32 v187, v187
	v_exp_f32_e32 v188, v188
	v_cmp_lt_i32_e32 vcc, 6, v212
	v_cmp_lt_i32_e64 s[92:93], 7, v212
	v_cmp_lt_i32_e64 s[94:95], 8, v212
	v_cndmask_b32_e32 v186, 0, v186, vcc
	v_cndmask_b32_e64 v187, 0, v187, s[92:93]
	v_cndmask_b32_e64 v188, 0, v188, s[94:95]
	v_add_f32_e32 v189, v176, v189
	v_add_f32_e32 v190, v176, v190
	v_add_f32_e32 v191, v176, v191
	v_exp_f32_e32 v189, v189
	v_exp_f32_e32 v190, v190
	v_exp_f32_e32 v191, v191
	v_cmp_lt_i32_e32 vcc, 9, v212
	v_cmp_lt_i32_e64 s[92:93], 10, v212
	v_cmp_lt_i32_e64 s[94:95], 11, v212
	v_cndmask_b32_e32 v189, 0, v189, vcc
	v_cndmask_b32_e64 v190, 0, v190, s[92:93]
	v_cndmask_b32_e64 v191, 0, v191, s[94:95]
	v_add_f32_e32 v192, v176, v192
	v_add_f32_e32 v193, v176, v193
	v_add_f32_e32 v194, v176, v194
	v_exp_f32_e32 v192, v192
	v_exp_f32_e32 v193, v193
	v_exp_f32_e32 v194, v194
	v_cmp_lt_i32_e32 vcc, 12, v212
	v_cmp_lt_i32_e64 s[92:93], 13, v212
	v_cmp_lt_i32_e64 s[94:95], 14, v212
	v_cndmask_b32_e32 v192, 0, v192, vcc
	v_cndmask_b32_e64 v193, 0, v193, s[92:93]
	v_cndmask_b32_e64 v194, 0, v194, s[94:95]
	v_add_f32_e32 v195, v176, v195
	v_add_f32_e32 v196, v176, v196
	v_add_f32_e32 v197, v176, v197
	v_exp_f32_e32 v195, v195
	v_exp_f32_e32 v196, v196
	v_exp_f32_e32 v197, v197
	v_cmp_lt_i32_e32 vcc, 15, v212
	v_cmp_lt_i32_e64 s[92:93], 16, v212
	v_cmp_lt_i32_e64 s[94:95], 17, v212
	v_cndmask_b32_e32 v195, 0, v195, vcc
	v_cndmask_b32_e64 v196, 0, v196, s[92:93]
	v_cndmask_b32_e64 v197, 0, v197, s[94:95]
	v_add_f32_e32 v198, v176, v198
	v_add_f32_e32 v199, v176, v199
	v_add_f32_e32 v200, v176, v200
	v_exp_f32_e32 v198, v198
	v_exp_f32_e32 v199, v199
	v_exp_f32_e32 v200, v200
	v_cmp_lt_i32_e32 vcc, 18, v212
	v_cmp_lt_i32_e64 s[92:93], 19, v212
	v_cmp_lt_i32_e64 s[94:95], 20, v212
	v_cndmask_b32_e32 v198, 0, v198, vcc
	v_cndmask_b32_e64 v199, 0, v199, s[92:93]
	v_cndmask_b32_e64 v200, 0, v200, s[94:95]
	v_add_f32_e32 v201, v176, v201
	v_add_f32_e32 v202, v176, v202
	v_add_f32_e32 v203, v176, v203
	v_exp_f32_e32 v201, v201
	v_exp_f32_e32 v202, v202
	v_exp_f32_e32 v203, v203
	v_cmp_lt_i32_e32 vcc, 21, v212
	v_cmp_lt_i32_e64 s[92:93], 22, v212
	v_cmp_lt_i32_e64 s[94:95], 23, v212
	v_cndmask_b32_e32 v201, 0, v201, vcc
	v_cndmask_b32_e64 v202, 0, v202, s[92:93]
	v_cndmask_b32_e64 v203, 0, v203, s[94:95]
	v_add_f32_e32 v204, v176, v204
	v_add_f32_e32 v205, v176, v205
	v_add_f32_e32 v206, v176, v206
	v_exp_f32_e32 v204, v204
	v_exp_f32_e32 v205, v205
	v_exp_f32_e32 v206, v206
	v_cmp_lt_i32_e32 vcc, 24, v212
	v_cmp_lt_i32_e64 s[92:93], 25, v212
	v_cmp_lt_i32_e64 s[94:95], 26, v212
	v_cndmask_b32_e32 v204, 0, v204, vcc
	v_cndmask_b32_e64 v205, 0, v205, s[92:93]
	v_cndmask_b32_e64 v206, 0, v206, s[94:95]
	v_add_f32_e32 v207, v176, v207
	v_add_f32_e32 v208, v176, v208
	v_add_f32_e32 v209, v176, v209
	v_exp_f32_e32 v207, v207
	v_exp_f32_e32 v208, v208
	v_exp_f32_e32 v209, v209
	v_cmp_lt_i32_e32 vcc, 27, v212
	v_cmp_lt_i32_e64 s[92:93], 28, v212
	v_cmp_lt_i32_e64 s[94:95], 29, v212
	v_cndmask_b32_e32 v207, 0, v207, vcc
	v_cndmask_b32_e64 v208, 0, v208, s[92:93]
	v_cndmask_b32_e64 v209, 0, v209, s[94:95]
	v_add_f32_e32 v210, v176, v210
	v_add_f32_e32 v211, v176, v211
	v_exp_f32_e32 v210, v210
	v_exp_f32_e32 v211, v211
	v_cmp_lt_i32_e32 vcc, 30, v212
	v_cmp_lt_i32_e64 s[92:93], 31, v212
	s_nop 0
	v_cndmask_b32_e32 v210, 0, v210, vcc
	v_cndmask_b32_e64 v211, 0, v211, s[92:93]
	v_cvt_pk_bf16_f32 v148, v180, v181
	v_cvt_pk_bf16_f32 v149, v182, v183
	v_cvt_pk_bf16_f32 v150, v184, v185
	v_cvt_pk_bf16_f32 v151, v186, v187
	ds_write_b128 v175, v[148:151]
	s_nop 0
	v_cvt_pk_bf16_f32 v148, v188, v189
	v_cvt_pk_bf16_f32 v149, v190, v191
	v_cvt_pk_bf16_f32 v150, v192, v193
	v_cvt_pk_bf16_f32 v151, v194, v195
	ds_write_b128 v175, v[148:151] offset:16
	s_nop 0
	v_cvt_pk_bf16_f32 v148, v196, v197
	v_cvt_pk_bf16_f32 v149, v198, v199
	v_cvt_pk_bf16_f32 v150, v200, v201
	v_cvt_pk_bf16_f32 v151, v202, v203
	ds_write_b128 v175, v[148:151] offset:32
	s_nop 0
	v_cvt_pk_bf16_f32 v148, v204, v205
	v_cvt_pk_bf16_f32 v149, v206, v207
	v_cvt_pk_bf16_f32 v150, v208, v209
	v_cvt_pk_bf16_f32 v151, v210, v211
	ds_write_b128 v175, v[148:151] offset:48
	s_branch .LBB0_213
; __device__ __forceinline__ unsigned pack2(float a, float b) { return (unsigned)f2bf(a) | ((unsigned)f2bf(b) << 16); }
; template <int DH, int MODE>
; __device__ void attn_item(const Params& p, int layer, int b, int blk, int head, char* smem) {
;     ...
; #pragma unroll 2
;         for (int s8 = 0; s8 < 4; ++s8) {
;           float4 va = s4[2 * s8], vb = s4[2 * s8 + 1];
;           float e[8] = {va.x, va.y, va.z, va.w, vb.x, vb.y, vb.z, vb.w};
;           float pv[8];
; #pragma unroll
;           for (int k = 0; k < 8; ++k) {
;             bool valid = (kpb + s8 * 8 + k) < qpos;
;             pv[k] = valid ? __builtin_amdgcn_exp2f(e[k] + offs) : 0.f;
;           }
;           uint4 ov;
;           ov.x = pack2(pv[0], pv[1]); ov.y = pack2(pv[2], pv[3]);
;           ov.z = pack2(pv[4], pv[5]); ov.w = pack2(pv[6], pv[7]);
;           *reinterpret_cast<uint4*>(prow + s8 * 16) = ov;
;         }
.Lsb_p2fast_3:
	v_add_f32_e32 v180, v176, v180
	v_add_f32_e32 v181, v176, v181
	v_add_f32_e32 v182, v176, v182
	v_add_f32_e32 v183, v176, v183
	v_exp_f32_e32 v180, v180
	v_exp_f32_e32 v181, v181
	v_exp_f32_e32 v182, v182
	v_exp_f32_e32 v183, v183
	v_add_f32_e32 v184, v176, v184
	v_add_f32_e32 v185, v176, v185
	v_add_f32_e32 v186, v176, v186
	v_add_f32_e32 v187, v176, v187
	v_exp_f32_e32 v184, v184
	v_exp_f32_e32 v185, v185
	v_exp_f32_e32 v186, v186
	v_exp_f32_e32 v187, v187
	v_add_f32_e32 v188, v176, v188
	v_add_f32_e32 v189, v176, v189
	v_add_f32_e32 v190, v176, v190
	v_add_f32_e32 v191, v176, v191
	v_exp_f32_e32 v188, v188
	v_exp_f32_e32 v189, v189
	v_exp_f32_e32 v190, v190
	v_exp_f32_e32 v191, v191
	v_add_f32_e32 v192, v176, v192
	v_add_f32_e32 v193, v176, v193
	v_add_f32_e32 v194, v176, v194
	v_add_f32_e32 v195, v176, v195
	v_exp_f32_e32 v192, v192
	v_exp_f32_e32 v193, v193
	v_exp_f32_e32 v194, v194
	v_exp_f32_e32 v195, v195
	v_add_f32_e32 v196, v176, v196
	v_add_f32_e32 v197, v176, v197
	v_add_f32_e32 v198, v176, v198
	v_add_f32_e32 v199, v176, v199
	v_exp_f32_e32 v196, v196
	v_exp_f32_e32 v197, v197
	v_exp_f32_e32 v198, v198
	v_exp_f32_e32 v199, v199
	v_add_f32_e32 v200, v176, v200
	v_add_f32_e32 v201, v176, v201
	v_add_f32_e32 v202, v176, v202
	v_add_f32_e32 v203, v176, v203
	v_exp_f32_e32 v200, v200
	v_exp_f32_e32 v201, v201
	v_exp_f32_e32 v202, v202
	v_exp_f32_e32 v203, v203
	v_add_f32_e32 v204, v176, v204
	v_add_f32_e32 v205, v176, v205
	v_add_f32_e32 v206, v176, v206
	v_add_f32_e32 v207, v176, v207
	v_exp_f32_e32 v204, v204
	v_exp_f32_e32 v205, v205
	v_exp_f32_e32 v206, v206
	v_exp_f32_e32 v207, v207
	v_add_f32_e32 v208, v176, v208
	v_add_f32_e32 v209, v176, v209
	v_add_f32_e32 v210, v176, v210
	v_add_f32_e32 v211, v176, v211
	v_exp_f32_e32 v208, v208
	v_exp_f32_e32 v209, v209
	v_exp_f32_e32 v210, v210
	v_exp_f32_e32 v211, v211
	s_nop 0
	v_cvt_pk_bf16_f32 v148, v180, v181
	v_cvt_pk_bf16_f32 v149, v182, v183
	v_cvt_pk_bf16_f32 v150, v184, v185
	v_cvt_pk_bf16_f32 v151, v186, v187
	ds_write_b128 v175, v[148:151]
	s_nop 0
	v_cvt_pk_bf16_f32 v148, v188, v189
	v_cvt_pk_bf16_f32 v149, v190, v191
	v_cvt_pk_bf16_f32 v150, v192, v193
	v_cvt_pk_bf16_f32 v151, v194, v195
	ds_write_b128 v175, v[148:151] offset:16
	s_nop 0
	v_cvt_pk_bf16_f32 v148, v196, v197
	v_cvt_pk_bf16_f32 v149, v198, v199
	v_cvt_pk_bf16_f32 v150, v200, v201
	v_cvt_pk_bf16_f32 v151, v202, v203
	ds_write_b128 v175, v[148:151] offset:32
	s_nop 0
	v_cvt_pk_bf16_f32 v148, v204, v205
	v_cvt_pk_bf16_f32 v149, v206, v207
	v_cvt_pk_bf16_f32 v150, v208, v209
	v_cvt_pk_bf16_f32 v151, v210, v211
	ds_write_b128 v175, v[148:151] offset:48
	s_branch .LBB0_213

; __device__ __forceinline__ unsigned pack2(float a, float b) { return (unsigned)f2bf(a) | ((unsigned)f2bf(b) << 16); }
; template <int DH, int MODE>
; __device__ void attn_item(const Params& p, int layer, int b, int blk, int head, char* smem) {
;     ...
;         float other = __shfl_xor(run, 1);
;         float offs = m_run + (half == 0 ? other : 0.f);
; #pragma unroll 2
;         for (int s8 = 0; s8 < 4; ++s8) {
;           float4 va = s4[2 * s8], vb = s4[2 * s8 + 1];
;           float e[8] = {va.x, va.y, va.z, va.w, vb.x, vb.y, vb.z, vb.w};
;           float pv[8];
; #pragma unroll
;           for (int k = 0; k < 8; ++k) {
;             bool valid = (kpb + s8 * 8 + k) < qpos;
;             pv[k] = valid ? __builtin_amdgcn_exp2f(e[k] + offs) : 0.f;
;           }
;           uint4 ov;
;           ov.x = pack2(pv[0], pv[1]); ov.y = pack2(pv[2], pv[3]);
;           ov.z = pack2(pv[4], pv[5]); ov.w = pack2(pv[6], pv[7]);
;           *reinterpret_cast<uint4*>(prow + s8 * 16) = ov;
;         }
.Lsb_p1done_2:
	ds_bpermute_b32 v147, v163, v146
	s_mov_b32 s88, 0
	v_mov_b32_e32 v175, v168
	v_mov_b32_e32 v177, v167
	s_waitcnt lgkmcnt(0)
	v_cndmask_b32_e64 v148, 0, v147, s[14:15]
	v_add_f32_e32 v176, v174, v148
	v_sub_u32_e32 v212, v144, v173
	v_add_u32_e32 v212, 0xffffc040, v212
	v_cmp_lt_i32_e32 vcc, 31, v212
	s_cmp_eq_u64 vcc, exec
	s_cbranch_scc1 .Lsb_p2fast_2
	v_add_f32_e32 v180, v176, v180
	v_add_f32_e32 v181, v176, v181
	v_add_f32_e32 v182, v176, v182
	v_exp_f32_e32 v180, v180
	v_exp_f32_e32 v181, v181
	v_exp_f32_e32 v182, v182
	v_cmp_lt_i32_e32 vcc, 0, v212
	v_cmp_lt_i32_e64 s[92:93], 1, v212
	v_cmp_lt_i32_e64 s[94:95], 2, v212
	v_cndmask_b32_e32 v180, 0, v180, vcc
	v_cndmask_b32_e64 v181, 0, v181, s[92:93]
	v_cndmask_b32_e64 v182, 0, v182, s[94:95]
	v_add_f32_e32 v183, v176, v183
	v_add_f32_e32 v184, v176, v184
	v_add_f32_e32 v185, v176, v185
	v_exp_f32_e32 v183, v183
	v_exp_f32_e32 v184, v184
	v_exp_f32_e32 v185, v185
	v_cmp_lt_i32_e32 vcc, 3, v212
	v_cmp_lt_i32_e64 s[92:93], 4, v212
	v_cmp_lt_i32_e64 s[94:95], 5, v212
	v_cndmask_b32_e32 v183, 0, v183, vcc
	v_cndmask_b32_e64 v184, 0, v184, s[92:93]
	v_cndmask_b32_e64 v185, 0, v185, s[94:95]
	v_add_f32_e32 v186, v176, v186
	v_add_f32_e32 v187, v176, v187
	v_add_f32_e32 v188, v176, v188
	v_exp_f32_e32 v186, v186
	v_exp_f32_e32 v187, v187
	v_exp_f32_e32 v188, v188
	v_cmp_lt_i32_e32 vcc, 6, v212
	v_cmp_lt_i32_e64 s[92:93], 7, v212
	v_cmp_lt_i32_e64 s[94:95], 8, v212
	v_cndmask_b32_e32 v186, 0, v186, vcc
	v_cndmask_b32_e64 v187, 0, v187, s[92:93]
	v_cndmask_b32_e64 v188, 0, v188, s[94:95]
	v_add_f32_e32 v189, v176, v189
	v_add_f32_e32 v190, v176, v190
	v_add_f32_e32 v191, v176, v191
	v_exp_f32_e32 v189, v189
	v_exp_f32_e32 v190, v190
	v_exp_f32_e32 v191, v191
	v_cmp_lt_i32_e32 vcc, 9, v212
	v_cmp_lt_i32_e64 s[92:93], 10, v212
	v_cmp_lt_i32_e64 s[94:95], 11, v212
	v_cndmask_b32_e32 v189, 0, v189, vcc
	v_cndmask_b32_e64 v190, 0, v190, s[92:93]
	v_cndmask_b32_e64 v191, 0, v191, s[94:95]
	v_add_f32_e32 v192, v176, v192
	v_add_f32_e32 v193, v176, v193
	v_add_f32_e32 v194, v176, v194
	v_exp_f32_e32 v192, v192
	v_exp_f32_e32 v193, v193
	v_exp_f32_e32 v194, v194
	v_cmp_lt_i32_e32 vcc, 12, v212
	v_cmp_lt_i32_e64 s[92:93], 13, v212
	v_cmp_lt_i32_e64 s[94:95], 14, v212
	v_cndmask_b32_e32 v192, 0, v192, vcc
	v_cndmask_b32_e64 v193, 0, v193, s[92:93]
	v_cndmask_b32_e64 v194, 0, v194, s[94:95]
	v_add_f32_e32 v195, v176, v195
	v_add_f32_e32 v196, v176, v196
	v_add_f32_e32 v197, v176, v197
	v_exp_f32_e32 v195, v195
	v_exp_f32_e32 v196, v196
	v_exp_f32_e32 v197, v197
	v_cmp_lt_i32_e32 vcc, 15, v212
	v_cmp_lt_i32_e64 s[92:93], 16, v212
	v_cmp_lt_i32_e64 s[94:95], 17, v212
	v_cndmask_b32_e32 v195, 0, v195, vcc
	v_cndmask_b32_e64 v196, 0, v196, s[92:93]
	v_cndmask_b32_e64 v197, 0, v197, s[94:95]
	v_add_f32_e32 v198, v176, v198
	v_add_f32_e32 v199, v176, v199
	v_add_f32_e32 v200, v176, v200
	v_exp_f32_e32 v198, v198
	v_exp_f32_e32 v199, v199
	v_exp_f32_e32 v200, v200
	v_cmp_lt_i32_e32 vcc, 18, v212
	v_cmp_lt_i32_e64 s[92:93], 19, v212
	v_cmp_lt_i32_e64 s[94:95], 20, v212
	v_cndmask_b32_e32 v198, 0, v198, vcc
	v_cndmask_b32_e64 v199, 0, v199, s[92:93]
	v_cndmask_b32_e64 v200, 0, v200, s[94:95]
	v_add_f32_e32 v201, v176, v201
	v_add_f32_e32 v202, v176, v202
	v_add_f32_e32 v203, v176, v203
	v_exp_f32_e32 v201, v201
	v_exp_f32_e32 v202, v202
	v_exp_f32_e32 v203, v203
	v_cmp_lt_i32_e32 vcc, 21, v212
	v_cmp_lt_i32_e64 s[92:93], 22, v212
	v_cmp_lt_i32_e64 s[94:95], 23, v212
	v_cndmask_b32_e32 v201, 0, v201, vcc
	v_cndmask_b32_e64 v202, 0, v202, s[92:93]
	v_cndmask_b32_e64 v203, 0, v203, s[94:95]
	v_add_f32_e32 v204, v176, v204
	v_add_f32_e32 v205, v176, v205
	v_add_f32_e32 v206, v176, v206
	v_exp_f32_e32 v204, v204
	v_exp_f32_e32 v205, v205
	v_exp_f32_e32 v206, v206
	v_cmp_lt_i32_e32 vcc, 24, v212
	v_cmp_lt_i32_e64 s[92:93], 25, v212
	v_cmp_lt_i32_e64 s[94:95], 26, v212
	v_cndmask_b32_e32 v204, 0, v204, vcc
	v_cndmask_b32_e64 v205, 0, v205, s[92:93]
	v_cndmask_b32_e64 v206, 0, v206, s[94:95]
	v_add_f32_e32 v207, v176, v207
	v_add_f32_e32 v208, v176, v208
	v_add_f32_e32 v209, v176, v209
	v_exp_f32_e32 v207, v207
	v_exp_f32_e32 v208, v208
	v_exp_f32_e32 v209, v209
	v_cmp_lt_i32_e32 vcc, 27, v212
	v_cmp_lt_i32_e64 s[92:93], 28, v212
	v_cmp_lt_i32_e64 s[94:95], 29, v212
	v_cndmask_b32_e32 v207, 0, v207, vcc
	v_cndmask_b32_e64 v208, 0, v208, s[92:93]
	v_cndmask_b32_e64 v209, 0, v209, s[94:95]
	v_add_f32_e32 v210, v176, v210
	v_add_f32_e32 v211, v176, v211
	v_exp_f32_e32 v210, v210
	v_exp_f32_e32 v211, v211
	v_cmp_lt_i32_e32 vcc, 30, v212
	v_cmp_lt_i32_e64 s[92:93], 31, v212
	s_nop 0
	v_cndmask_b32_e32 v210, 0, v210, vcc
	v_cndmask_b32_e64 v211, 0, v211, s[92:93]
	v_cvt_pk_bf16_f32 v148, v180, v181
	v_cvt_pk_bf16_f32 v149, v182, v183
	v_cvt_pk_bf16_f32 v150, v184, v185
	v_cvt_pk_bf16_f32 v151, v186, v187
	ds_write_b128 v175, v[148:151]
	s_nop 0
	v_cvt_pk_bf16_f32 v148, v188, v189
	v_cvt_pk_bf16_f32 v149, v190, v191
	v_cvt_pk_bf16_f32 v150, v192, v193
	v_cvt_pk_bf16_f32 v151, v194, v195
	ds_write_b128 v175, v[148:151] offset:16
	s_nop 0
	v_cvt_pk_bf16_f32 v148, v196, v197
	v_cvt_pk_bf16_f32 v149, v198, v199
	v_cvt_pk_bf16_f32 v150, v200, v201
	v_cvt_pk_bf16_f32 v151, v202, v203
	ds_write_b128 v175, v[148:151] offset:32
	s_nop 0
	v_cvt_pk_bf16_f32 v148, v204, v205
	v_cvt_pk_bf16_f32 v149, v206, v207
	v_cvt_pk_bf16_f32 v150, v208, v209
	v_cvt_pk_bf16_f32 v151, v210, v211
	ds_write_b128 v175, v[148:151] offset:48
	s_branch .LBB0_534

; __device__ __forceinline__ unsigned pack2(float a, float b) { return (unsigned)f2bf(a) | ((unsigned)f2bf(b) << 16); }
; template <int DH, int MODE>
; __device__ void attn_item(const Params& p, int layer, int b, int blk, int head, char* smem) {
;     ...
;         float other = __shfl_xor(run, 1);
;         float offs = m_run + (half == 0 ? other : 0.f);
; #pragma unroll 2
;         for (int s8 = 0; s8 < 4; ++s8) {
;           float4 va = s4[2 * s8], vb = s4[2 * s8 + 1];
;           float e[8] = {va.x, va.y, va.z, va.w, vb.x, vb.y, vb.z, vb.w};
;           float pv[8];
; #pragma unroll
;           for (int k = 0; k < 8; ++k) {
;             bool valid = (kpb + s8 * 8 + k) < qpos;
;             pv[k] = valid ? __builtin_amdgcn_exp2f(e[k] + offs) : 0.f;
;           }
;           uint4 ov;
;           ov.x = pack2(pv[0], pv[1]); ov.y = pack2(pv[2], pv[3]);
;           ov.z = pack2(pv[4], pv[5]); ov.w = pack2(pv[6], pv[7]);
;           *reinterpret_cast<uint4*>(prow + s8 * 16) = ov;
;         }
.Lsb_p1done_0:
	ds_bpermute_b32 v147, v163, v146
	s_mov_b32 s81, 0
	v_mov_b32_e32 v175, v168
	v_mov_b32_e32 v177, v167
	s_waitcnt lgkmcnt(0)
	v_cndmask_b32_e64 v148, 0, v147, s[8:9]
	v_add_f32_e32 v176, v174, v148
	v_sub_u32_e32 v212, v144, v173
	v_add_u32_e32 v212, 0xffffc040, v212
	v_cmp_lt_i32_e32 vcc, 31, v212
	s_cmp_eq_u64 vcc, exec
	s_cbranch_scc1 .Lsb_p2fast_0
	v_add_f32_e32 v180, v176, v180
	v_add_f32_e32 v181, v176, v181
	v_add_f32_e32 v182, v176, v182
	v_exp_f32_e32 v180, v180
	v_exp_f32_e32 v181, v181
	v_exp_f32_e32 v182, v182
	v_cmp_lt_i32_e32 vcc, 0, v212
	v_cmp_lt_i32_e64 s[92:93], 1, v212
	v_cmp_lt_i32_e64 s[94:95], 2, v212
	v_cndmask_b32_e32 v180, 0, v180, vcc
	v_cndmask_b32_e64 v181, 0, v181, s[92:93]
	v_cndmask_b32_e64 v182, 0, v182, s[94:95]
	v_add_f32_e32 v183, v176, v183
	v_add_f32_e32 v184, v176, v184
	v_add_f32_e32 v185, v176, v185
	v_exp_f32_e32 v183, v183
	v_exp_f32_e32 v184, v184
	v_exp_f32_e32 v185, v185
	v_cmp_lt_i32_e32 vcc, 3, v212
	v_cmp_lt_i32_e64 s[92:93], 4, v212
	v_cmp_lt_i32_e64 s[94:95], 5, v212
	v_cndmask_b32_e32 v183, 0, v183, vcc
	v_cndmask_b32_e64 v184, 0, v184, s[92:93]
	v_cndmask_b32_e64 v185, 0, v185, s[94:95]
	v_add_f32_e32 v186, v176, v186
	v_add_f32_e32 v187, v176, v187
	v_add_f32_e32 v188, v176, v188
	v_exp_f32_e32 v186, v186
	v_exp_f32_e32 v187, v187
	v_exp_f32_e32 v188, v188
	v_cmp_lt_i32_e32 vcc, 6, v212
	v_cmp_lt_i32_e64 s[92:93], 7, v212
	v_cmp_lt_i32_e64 s[94:95], 8, v212
	v_cndmask_b32_e32 v186, 0, v186, vcc
	v_cndmask_b32_e64 v187, 0, v187, s[92:93]
	v_cndmask_b32_e64 v188, 0, v188, s[94:95]
	v_add_f32_e32 v189, v176, v189
	v_add_f32_e32 v190, v176, v190
	v_add_f32_e32 v191, v176, v191
	v_exp_f32_e32 v189, v189
	v_exp_f32_e32 v190, v190
	v_exp_f32_e32 v191, v191
	v_cmp_lt_i32_e32 vcc, 9, v212
	v_cmp_lt_i32_e64 s[92:93], 10, v212
	v_cmp_lt_i32_e64 s[94:95], 11, v212
	v_cndmask_b32_e32 v189, 0, v189, vcc
	v_cndmask_b32_e64 v190, 0, v190, s[92:93]
	v_cndmask_b32_e64 v191, 0, v191, s[94:95]
	v_add_f32_e32 v192, v176, v192
	v_add_f32_e32 v193, v176, v193
	v_add_f32_e32 v194, v176, v194
	v_exp_f32_e32 v192, v192
	v_exp_f32_e32 v193, v193
	v_exp_f32_e32 v194, v194
	v_cmp_lt_i32_e32 vcc, 12, v212
	v_cmp_lt_i32_e64 s[92:93], 13, v212
	v_cmp_lt_i32_e64 s[94:95], 14, v212
	v_cndmask_b32_e32 v192, 0, v192, vcc
	v_cndmask_b32_e64 v193, 0, v193, s[92:93]
	v_cndmask_b32_e64 v194, 0, v194, s[94:95]
	v_add_f32_e32 v195, v176, v195
	v_add_f32_e32 v196, v176, v196
	v_add_f32_e32 v197, v176, v197
	v_exp_f32_e32 v195, v195
	v_exp_f32_e32 v196, v196
	v_exp_f32_e32 v197, v197
	v_cmp_lt_i32_e32 vcc, 15, v212
	v_cmp_lt_i32_e64 s[92:93], 16, v212
	v_cmp_lt_i32_e64 s[94:95], 17, v212
	v_cndmask_b32_e32 v195, 0, v195, vcc
	v_cndmask_b32_e64 v196, 0, v196, s[92:93]
	v_cndmask_b32_e64 v197, 0, v197, s[94:95]
	v_add_f32_e32 v198, v176, v198
	v_add_f32_e32 v199, v176, v199
	v_add_f32_e32 v200, v176, v200
	v_exp_f32_e32 v198, v198
	v_exp_f32_e32 v199, v199
	v_exp_f32_e32 v200, v200
	v_cmp_lt_i32_e32 vcc, 18, v212
	v_cmp_lt_i32_e64 s[92:93], 19, v212
	v_cmp_lt_i32_e64 s[94:95], 20, v212
	v_cndmask_b32_e32 v198, 0, v198, vcc
	v_cndmask_b32_e64 v199, 0, v199, s[92:93]
	v_cndmask_b32_e64 v200, 0, v200, s[94:95]
	v_add_f32_e32 v201, v176, v201
	v_add_f32_e32 v202, v176, v202
	v_add_f32_e32 v203, v176, v203
	v_exp_f32_e32 v201, v201
	v_exp_f32_e32 v202, v202
	v_exp_f32_e32 v203, v203
	v_cmp_lt_i32_e32 vcc, 21, v212
	v_cmp_lt_i32_e64 s[92:93], 22, v212
	v_cmp_lt_i32_e64 s[94:95], 23, v212
	v_cndmask_b32_e32 v201, 0, v201, vcc
	v_cndmask_b32_e64 v202, 0, v202, s[92:93]
	v_cndmask_b32_e64 v203, 0, v203, s[94:95]
	v_add_f32_e32 v204, v176, v204
	v_add_f32_e32 v205, v176, v205
	v_add_f32_e32 v206, v176, v206
	v_exp_f32_e32 v204, v204
	v_exp_f32_e32 v205, v205
	v_exp_f32_e32 v206, v206
	v_cmp_lt_i32_e32 vcc, 24, v212
	v_cmp_lt_i32_e64 s[92:93], 25, v212
	v_cmp_lt_i32_e64 s[94:95], 26, v212
	v_cndmask_b32_e32 v204, 0, v204, vcc
	v_cndmask_b32_e64 v205, 0, v205, s[92:93]
	v_cndmask_b32_e64 v206, 0, v206, s[94:95]
	v_add_f32_e32 v207, v176, v207
	v_add_f32_e32 v208, v176, v208
	v_add_f32_e32 v209, v176, v209
	v_exp_f32_e32 v207, v207
	v_exp_f32_e32 v208, v208
	v_exp_f32_e32 v209, v209
	v_cmp_lt_i32_e32 vcc, 27, v212
	v_cmp_lt_i32_e64 s[92:93], 28, v212
	v_cmp_lt_i32_e64 s[94:95], 29, v212
	v_cndmask_b32_e32 v207, 0, v207, vcc
	v_cndmask_b32_e64 v208, 0, v208, s[92:93]
	v_cndmask_b32_e64 v209, 0, v209, s[94:95]
	v_add_f32_e32 v210, v176, v210
	v_add_f32_e32 v211, v176, v211
	v_exp_f32_e32 v210, v210
	v_exp_f32_e32 v211, v211
	v_cmp_lt_i32_e32 vcc, 30, v212
	v_cmp_lt_i32_e64 s[92:93], 31, v212
	s_nop 0
	v_cndmask_b32_e32 v210, 0, v210, vcc
	v_cndmask_b32_e64 v211, 0, v211, s[92:93]
	v_cvt_pk_bf16_f32 v148, v180, v181
	v_cvt_pk_bf16_f32 v149, v182, v183
	v_cvt_pk_bf16_f32 v150, v184, v185
	v_cvt_pk_bf16_f32 v151, v186, v187
	ds_write_b128 v175, v[148:151]
	s_nop 0
	v_cvt_pk_bf16_f32 v148, v188, v189
	v_cvt_pk_bf16_f32 v149, v190, v191
	v_cvt_pk_bf16_f32 v150, v192, v193
	v_cvt_pk_bf16_f32 v151, v194, v195
	ds_write_b128 v175, v[148:151] offset:16
	s_nop 0
	v_cvt_pk_bf16_f32 v148, v196, v197
	v_cvt_pk_bf16_f32 v149, v198, v199
	v_cvt_pk_bf16_f32 v150, v200, v201
	v_cvt_pk_bf16_f32 v151, v202, v203
	ds_write_b128 v175, v[148:151] offset:32
	s_nop 0
	v_cvt_pk_bf16_f32 v148, v204, v205
	v_cvt_pk_bf16_f32 v149, v206, v207
	v_cvt_pk_bf16_f32 v150, v208, v209
	v_cvt_pk_bf16_f32 v151, v210, v211
	ds_write_b128 v175, v[148:151] offset:48
	s_branch .LBB0_1176
